# fused-norm epilogue (out-GEMM / MLP-down): the 8 row-statistics partials are loaded together and summed in the original order, instead of 8 serialized sc1 load-wait-add round trips
# baseline (speedup 1.0000x reference)
;     __device__ __forceinline__ void fuse_tail(f32x4 (&acc)[2][2][4][2], const float (&ssq)[2][4], const Unit& u, int wr, int wc, int fr, int fq, int mi, int row0, int col0) const {
;     ...
;         asm volatile("s_waitcnt lgkmcnt(0)" ::: "memory"); __builtin_amdgcn_s_barrier(); asm volatile("" ::: "memory");
;         if (lane < 32) { float t = 0.f;
; #pragma unroll
;             for (int k = 0; k < 8; ++k) t += __builtin_bit_cast(float, __hip_atomic_load(slots + k, __ATOMIC_RELAXED, __HIP_MEMORY_SCOPE_AGENT));
;             S[row] = rsqrtf(t * (1.f / D) + 1e-6f); }
;         asm volatile("s_waitcnt lgkmcnt(0)" ::: "memory"); __builtin_amdgcn_s_barrier(); asm volatile("" ::: "memory");
.LBB9_1196:
	s_waitcnt lgkmcnt(0)
	s_barrier
	s_and_saveexec_b64 s[44:45], s[40:41]
	s_cbranch_execz .LBB9_1198
	global_load_dword v4, v[2:3], off sc1
	global_load_dword v5, v[2:3], off offset:4 sc1
	global_load_dword v7, v[2:3], off offset:8 sc1
	global_load_dword v8, v[2:3], off offset:12 sc1
	global_load_dword v9, v[2:3], off offset:16 sc1
	global_load_dword v130, v[2:3], off offset:20 sc1
	global_load_dword v131, v[2:3], off offset:24 sc1
	global_load_dword v132, v[2:3], off offset:28 sc1
	s_mov_b32 s3, 0x800000
	s_waitcnt vmcnt(7)
	v_add_f32_e32 v4, 0, v4
	s_waitcnt vmcnt(6)
	v_add_f32_e32 v4, v4, v5
	s_waitcnt vmcnt(5)
	v_add_f32_e32 v4, v4, v7
	s_waitcnt vmcnt(4)
	v_add_f32_e32 v4, v4, v8
	s_waitcnt vmcnt(3)
	v_add_f32_e32 v4, v4, v9
	s_waitcnt vmcnt(2)
	v_add_f32_e32 v4, v4, v130
	s_waitcnt vmcnt(1)
	v_add_f32_e32 v4, v4, v131
	s_waitcnt vmcnt(0)
	v_add_f32_e32 v2, v4, v132
	v_fmamk_f32 v2, v2, 0x3a000000, v238
	v_cmp_gt_f32_e32 vcc, s3, v2
	v_mul_f32_e32 v3, 0x4b800000, v2
	s_nop 0
	v_cndmask_b32_e32 v2, v2, v3, vcc
	v_rsq_f32_e32 v2, v2
	s_nop 0
	v_mul_f32_e32 v3, 0x45800000, v2
	v_cndmask_b32_e32 v2, v2, v3, vcc
	v_lshl_add_u32 v3, v6, 2, 0
	v_add_u32_e32 v3, 0x22000, v3
	ds_write_b32 v3, v2

;     __device__ __forceinline__ void fuse_tail(f32x4 (&acc)[2][2][4][2], const float (&ssq)[2][4], const Unit& u, int wr, int wc, int fr, int fq, int mi, int row0, int col0) const {
;     ...
;         asm volatile("s_waitcnt lgkmcnt(0)" ::: "memory"); __builtin_amdgcn_s_barrier(); asm volatile("" ::: "memory");
;         if (lane < 32) { float t = 0.f;
; #pragma unroll
;             for (int k = 0; k < 8; ++k) t += __builtin_bit_cast(float, __hip_atomic_load(slots + k, __ATOMIC_RELAXED, __HIP_MEMORY_SCOPE_AGENT));
;             S[row] = rsqrtf(t * (1.f / D) + 1e-6f); }
;         asm volatile("s_waitcnt lgkmcnt(0)" ::: "memory"); __builtin_amdgcn_s_barrier(); asm volatile("" ::: "memory");
.LBB9_1271:
	s_waitcnt lgkmcnt(0)
	s_barrier
	s_and_saveexec_b64 s[46:47], s[0:1]
	s_cbranch_execz .LBB9_1273
	global_load_dword v5, v[2:3], off sc1
	global_load_dword v6, v[2:3], off offset:4 sc1
	global_load_dword v7, v[2:3], off offset:8 sc1
	global_load_dword v8, v[2:3], off offset:12 sc1
	global_load_dword v9, v[2:3], off offset:16 sc1
	global_load_dword v130, v[2:3], off offset:20 sc1
	global_load_dword v131, v[2:3], off offset:24 sc1
	global_load_dword v132, v[2:3], off offset:28 sc1
	s_waitcnt vmcnt(7)
	v_add_f32_e32 v5, 0, v5
	s_waitcnt vmcnt(6)
	v_add_f32_e32 v5, v5, v6
	s_waitcnt vmcnt(5)
	v_add_f32_e32 v5, v5, v7
	s_waitcnt vmcnt(4)
	v_add_f32_e32 v5, v5, v8
	s_waitcnt vmcnt(3)
	v_add_f32_e32 v5, v5, v9
	s_waitcnt vmcnt(2)
	v_add_f32_e32 v5, v5, v130
	s_waitcnt vmcnt(1)
	v_add_f32_e32 v5, v5, v131
	s_waitcnt vmcnt(0)
	v_add_f32_e32 v2, v5, v132
	v_fmamk_f32 v2, v2, 0x3a000000, v238
	v_cmp_gt_f32_e32 vcc, s91, v2
	v_mul_f32_e32 v3, 0x4b800000, v2
	s_nop 0
	v_cndmask_b32_e32 v2, v2, v3, vcc
	v_rsq_f32_e32 v2, v2
	s_nop 0
	v_mul_f32_e32 v3, 0x45800000, v2
	v_cndmask_b32_e32 v2, v2, v3, vcc
	v_lshl_add_u32 v3, v4, 2, 0
	v_add_u32_e32 v3, 0x22000, v3
	ds_write_b32 v3, v2

;     __device__ __forceinline__ void fuse_tail(f32x4 (&acc)[2][2][4][2], const float (&ssq)[2][4], const Unit& u, int wr, int wc, int fr, int fq, int mi, int row0, int col0) const {
;     ...
;         asm volatile("s_waitcnt lgkmcnt(0)" ::: "memory"); __builtin_amdgcn_s_barrier(); asm volatile("" ::: "memory");
;         if (lane < 32) { float t = 0.f;
; #pragma unroll
;             for (int k = 0; k < 8; ++k) t += __builtin_bit_cast(float, __hip_atomic_load(slots + k, __ATOMIC_RELAXED, __HIP_MEMORY_SCOPE_AGENT));
;             S[row] = rsqrtf(t * (1.f / D) + 1e-6f); }
;         asm volatile("s_waitcnt lgkmcnt(0)" ::: "memory"); __builtin_amdgcn_s_barrier(); asm volatile("" ::: "memory");
.LBB9_1593:
	s_waitcnt lgkmcnt(0)
	s_barrier
	s_and_saveexec_b64 s[44:45], s[40:41]
	s_cbranch_execz .LBB9_1595
	global_load_dword v4, v[2:3], off sc1
	global_load_dword v5, v[2:3], off offset:4 sc1
	global_load_dword v7, v[2:3], off offset:8 sc1
	global_load_dword v8, v[2:3], off offset:12 sc1
	global_load_dword v9, v[2:3], off offset:16 sc1
	global_load_dword v130, v[2:3], off offset:20 sc1
	global_load_dword v131, v[2:3], off offset:24 sc1
	global_load_dword v132, v[2:3], off offset:28 sc1
	s_waitcnt vmcnt(7)
	v_add_f32_e32 v4, 0, v4
	s_waitcnt vmcnt(6)
	v_add_f32_e32 v4, v4, v5
	s_waitcnt vmcnt(5)
	v_add_f32_e32 v4, v4, v7
	s_waitcnt vmcnt(4)
	v_add_f32_e32 v4, v4, v8
	s_waitcnt vmcnt(3)
	v_add_f32_e32 v4, v4, v9
	s_waitcnt vmcnt(2)
	v_add_f32_e32 v4, v4, v130
	s_waitcnt vmcnt(1)
	v_add_f32_e32 v4, v4, v131
	s_waitcnt vmcnt(0)
	v_add_f32_e32 v2, v4, v132
	v_fmamk_f32 v2, v2, 0x3a000000, v238
	v_cmp_gt_f32_e32 vcc, s94, v2
	v_mul_f32_e32 v3, 0x4b800000, v2
	s_nop 0
	v_cndmask_b32_e32 v2, v2, v3, vcc
	v_rsq_f32_e32 v2, v2
	s_nop 0
	v_mul_f32_e32 v3, 0x45800000, v2
	v_cndmask_b32_e32 v2, v2, v3, vcc
	v_lshl_add_u32 v3, v6, 2, 0
	v_add_u32_e32 v3, 0x22000, v3
	ds_write_b32 v3, v2

;     __device__ __forceinline__ void fuse_tail(f32x4 (&acc)[2][2][4][2], const float (&ssq)[2][4], const Unit& u, int wr, int wc, int fr, int fq, int mi, int row0, int col0) const {
;     ...
;         asm volatile("s_waitcnt lgkmcnt(0)" ::: "memory"); __builtin_amdgcn_s_barrier(); asm volatile("" ::: "memory");
;         if (lane < 32) { float t = 0.f;
; #pragma unroll
;             for (int k = 0; k < 8; ++k) t += __builtin_bit_cast(float, __hip_atomic_load(slots + k, __ATOMIC_RELAXED, __HIP_MEMORY_SCOPE_AGENT));
;             S[row] = rsqrtf(t * (1.f / D) + 1e-6f); }
;         asm volatile("s_waitcnt lgkmcnt(0)" ::: "memory"); __builtin_amdgcn_s_barrier(); asm volatile("" ::: "memory");
.LBB9_1664:
	s_waitcnt lgkmcnt(0)
	s_barrier
	s_and_saveexec_b64 s[44:45], s[0:1]
	s_cbranch_execz .LBB9_1666
	global_load_dword v5, v[2:3], off sc1
	global_load_dword v6, v[2:3], off offset:4 sc1
	global_load_dword v7, v[2:3], off offset:8 sc1
	global_load_dword v8, v[2:3], off offset:12 sc1
	global_load_dword v9, v[2:3], off offset:16 sc1
	global_load_dword v130, v[2:3], off offset:20 sc1
	global_load_dword v131, v[2:3], off offset:24 sc1
	global_load_dword v132, v[2:3], off offset:28 sc1
	s_waitcnt vmcnt(7)
	v_add_f32_e32 v5, 0, v5
	s_waitcnt vmcnt(6)
	v_add_f32_e32 v5, v5, v6
	s_waitcnt vmcnt(5)
	v_add_f32_e32 v5, v5, v7
	s_waitcnt vmcnt(4)
	v_add_f32_e32 v5, v5, v8
	s_waitcnt vmcnt(3)
	v_add_f32_e32 v5, v5, v9
	s_waitcnt vmcnt(2)
	v_add_f32_e32 v5, v5, v130
	s_waitcnt vmcnt(1)
	v_add_f32_e32 v5, v5, v131
	s_waitcnt vmcnt(0)
	v_add_f32_e32 v2, v5, v132
	v_fmamk_f32 v2, v2, 0x3a000000, v238
	v_cmp_gt_f32_e32 vcc, s56, v2
	v_mul_f32_e32 v3, 0x4b800000, v2
	s_nop 0
	v_cndmask_b32_e32 v2, v2, v3, vcc
	v_rsq_f32_e32 v2, v2
	s_nop 0
	v_mul_f32_e32 v3, 0x45800000, v2
	v_cndmask_b32_e32 v2, v2, v3, vcc
	v_lshl_add_u32 v3, v4, 2, 0
	v_add_u32_e32 v3, 0x22000, v3
	ds_write_b32 v3, v2
